# ffn1 GEMM third round: tile shared by two workgroups, each computes one 128-column half; the other half's B stage loads, fragment reads, MFMAs and stores removed (vmcnt 8 to 6)
# speedup vs baseline: 1.0059x; 1.0026x over previous
.LBB0_154:
	s_lshl_b32 s6, s6, 5
	s_and_b32 s10, s6, 0x60
	s_add_i32 m0, s27, 0x18000
	v_lshl_add_u64 v[6:7], v[6:7], 0, s[2:3]
	s_lshl_b32 s8, s1, 13
	s_lshl_b32 s9, s10, 7
	s_waitcnt vmcnt(2)
	s_barrier
	global_load_lds_dwordx4 v[6:7], off
	v_lshl_add_u64 v[4:5], v[4:5], 0, s[2:3]
	s_add_i32 m0, s27, 0x1a000
	s_add_i32 s34, s27, 0x8000
	s_add_i32 s35, s27, 0xa000
	global_load_lds_dwordx4 v[4:5], off
	v_lshl_add_u64 v[0:1], v[0:1], 0, s[2:3]
	s_mov_b32 m0, s34
	s_add_u32 s6, s20, 0x40080
	global_load_lds_dwordx4 v[0:1], off
	v_lshl_add_u64 v[0:1], v[2:3], 0, s[2:3]
	s_mov_b32 m0, s35
	s_addc_u32 s7, s21, 0
	global_load_lds_dwordx4 v[0:1], off
	s_add_i32 m0, s27, 0x1c000
	v_lshl_add_u64 v[0:1], s[6:7], 0, v[128:129]
	global_load_lds_dwordx4 v[0:1], off
	v_lshl_add_u64 v[0:1], s[6:7], 0, v[138:139]
	s_add_i32 m0, s27, 0x1e000
	s_cmpk_lt_u32 s0, 0x100
	global_load_lds_dwordx4 v[0:1], off
	v_lshrrev_b32_e32 v1, 1, v8
	v_and_b32_e32 v1, 24, v1
	v_and_b32_e32 v0, 15, v8
	v_lshlrev_b32_e32 v2, 1, v1
	v_lshl_or_b32 v150, s1, 6, v0
	v_lshl_or_b32 v0, v0, 6, v2
	v_lshlrev_b32_e32 v2, 2, v8
	v_and_b32_e32 v2, 32, v2
	v_bitop3_b32 v3, v0, s8, v2 bitop3:0xde
	v_bitop3_b32 v151, v0, s9, v2 bitop3:0xde
	v_lshlrev_b32_e32 v0, 14, v13
	v_and_b32_e32 v0, 0xffff8000, v0
	v_or_b32_e32 v152, s10, v1
	v_lshl_add_u32 v0, v12, 11, v0
	v_and_b32_e32 v1, 1, v13
	v_lshl_or_b32 v0, v1, 6, v0
	v_lshl_add_u32 v144, v14, 1, v0
	v_lshlrev_b32_e32 v0, 14, v9
	v_and_b32_e32 v0, 0xffff8000, v0
	s_waitcnt vmcnt(6)
	s_cselect_b64 s[6:7], -1, 0
	s_waitcnt lgkmcnt(0)
	s_ashr_i32 s36, s33, 31
	v_lshl_add_u32 v0, v10, 11, v0
	v_and_b32_e32 v1, 1, v9
	s_add_u32 s8, s84, 0xc2ca000
	v_lshl_or_b32 v0, v1, 6, v0
	v_readlane_b32 s0, v252, 22
	s_addc_u32 s9, s85, 0
	v_mov_b32_e32 v145, v129
	v_lshl_add_u32 v146, v11, 1, v0
	v_mov_b32_e32 v147, v129
	s_mov_b32 s37, 0
	v_add_u32_e32 v153, 0, v3
	v_readlane_b32 s38, v252, 21
	s_mov_b32 s39, s0
	s_barrier
	v_readlane_b32 s1, v252, 23
	s_mov_b32 s70, 0
	s_mov_b32 s71, 0
	s_branch .LBB0_157

.LBB0_156:
	s_mov_b32 s71, s70
	s_andn2_b64 vcc, exec, s[0:1]
	s_mov_b32 s38, s10
	s_mov_b32 s39, s12
	s_mov_b64 s[20:21], s[16:17]
	s_mov_b64 s[18:19], s[14:15]
	s_cbranch_vccz .LBB0_166
.LBB0_157:
	s_add_i32 s37, s37, 1
	s_mul_i32 s0, s37, s36
	s_mul_hi_u32 s1, s37, s33
	s_add_i32 s1, s1, s0
	s_mul_i32 s0, s37, s33
	v_readlane_b32 s11, v252, 0
	s_add_u32 s14, s0, s11
	v_readlane_b32 s0, v252, 10
	s_addc_u32 s15, s1, s0
	s_cmp_eq_u32 s37, 2
	s_cbranch_scc0 .Lq_full_B
	s_lshr_b32 s14, s11, 1
	s_addk_i32 s14, 0x200
	s_mov_b32 s15, 0
	s_and_b32 s70, s11, 1
	s_add_i32 s70, s70, 1
	s_branch .Lq_cont_B
.Lq_full_B:
	s_mov_b32 s70, 0
.Lq_cont_B:
	v_mov_b64_e32 v[0:1], 0x280
	v_cmp_lt_i64_e64 s[0:1], s[14:15], v[0:1]
	v_mov_b64_e32 v[0:1], 0x27f
	v_cmp_gt_i64_e32 vcc, s[14:15], v[0:1]
	s_cbranch_vccnz .LBB0_159
	s_ashr_i32 s10, s14, 31
	s_lshr_b32 s10, s10, 29
	s_add_i32 s10, s14, s10
	s_ashr_i32 s11, s10, 3
	s_and_b32 s10, s10, -8
	s_sub_i32 s10, s14, s10
	s_cmp_lt_i32 s10, 0
	s_movk_i32 s12, 0x51
	s_cselect_b32 s12, s12, 0x50
	s_mul_i32 s10, s12, s10
	s_add_i32 s10, s10, s11
	s_ashr_i32 s11, s10, 31
	s_lshr_b32 s11, s11, 25
	s_add_i32 s11, s10, s11
	s_ashr_i32 s12, s11, 7
	s_lshl_b32 s12, s12, 3
	s_sub_i32 s13, 40, s12
	s_min_i32 s13, s13, 8
	s_abs_i32 s14, s13
	v_cvt_f32_u32_e32 v0, s14
	s_sub_i32 s16, 0, s14
	s_and_b32 s11, s11, 0xffffff80
	s_sub_i32 s11, s10, s11
	v_rcp_iflag_f32_e32 v0, v0
	s_abs_i32 s10, s11
	s_xor_b32 s15, s11, s13
	s_ashr_i32 s15, s15, 31
	v_mul_f32_e32 v0, 0x4f7ffffe, v0
	v_cvt_u32_f32_e32 v0, v0
	s_nop 0
	v_readfirstlane_b32 s17, v0
	s_mul_i32 s16, s16, s17
	s_mul_hi_u32 s16, s17, s16
	s_add_i32 s17, s17, s16
	s_mul_hi_u32 s16, s10, s17
	s_mul_i32 s17, s16, s14
	s_sub_i32 s10, s10, s17
	s_add_i32 s22, s16, 1
	s_sub_i32 s17, s10, s14
	s_cmp_ge_u32 s10, s14
	s_cselect_b32 s16, s22, s16
	s_cselect_b32 s10, s17, s10
	s_add_i32 s17, s16, 1
	s_cmp_ge_u32 s10, s14
	s_cselect_b32 s10, s17, s16
	s_xor_b32 s10, s10, s15
	s_sub_i32 s10, s10, s15
	s_mul_i32 s13, s10, s13
	s_sub_i32 s11, s11, s13
	s_add_i32 s12, s11, s12
.LBB0_159:
	s_ashr_i32 s13, s12, 31
	s_lshl_b64 s[14:15], s[12:13], 19
	v_readlane_b32 s16, v254, 36
	v_readlane_b32 s17, v254, 37
	s_add_u32 s14, s16, s14
	s_addc_u32 s15, s17, s15
	s_and_b64 s[16:17], s[0:1], exec
	s_cselect_b32 s13, s15, s19
	s_cselect_b32 s40, s14, s18
	s_ashr_i32 s11, s10, 31
	s_lshl_b64 s[16:17], s[10:11], 19
	s_add_u32 s16, s24, s16
	s_addc_u32 s17, s25, s17
	s_and_b64 s[22:23], s[0:1], exec
	s_cselect_b32 s11, s17, s21
	s_cselect_b32 s41, s16, s20
	s_add_u32 s18, s18, 0x40080
	s_addc_u32 s19, s19, 0
	s_add_u32 s42, s20, 0x100
	v_mov_b32_e32 v0, 0
	s_addc_u32 s43, s21, 0
	s_mov_b32 s44, -2
	v_mov_b32_e32 v1, v0
	v_mov_b32_e32 v2, v0
	v_mov_b32_e32 v3, v0
	v_mov_b32_e32 v4, v0
	v_mov_b32_e32 v5, v0
	v_mov_b32_e32 v6, v0
	v_mov_b32_e32 v7, v0
	v_mov_b32_e32 v16, v0
	v_mov_b32_e32 v17, v0
	v_mov_b32_e32 v18, v0
	v_mov_b32_e32 v19, v0
	v_mov_b32_e32 v20, v0
	v_mov_b32_e32 v21, v0
	v_mov_b32_e32 v22, v0
	v_mov_b32_e32 v23, v0
	v_mov_b32_e32 v32, v0
	v_mov_b32_e32 v33, v0
	v_mov_b32_e32 v34, v0
	v_mov_b32_e32 v35, v0
	v_mov_b32_e32 v36, v0
	v_mov_b32_e32 v37, v0
	v_mov_b32_e32 v38, v0
	v_mov_b32_e32 v39, v0
	v_mov_b32_e32 v48, v0
	v_mov_b32_e32 v49, v0
	v_mov_b32_e32 v50, v0
	v_mov_b32_e32 v51, v0
	v_mov_b32_e32 v52, v0
	v_mov_b32_e32 v53, v0
	v_mov_b32_e32 v54, v0
	v_mov_b32_e32 v55, v0
	v_mov_b32_e32 v8, v0
	v_mov_b32_e32 v9, v0
	v_mov_b32_e32 v10, v0
	v_mov_b32_e32 v11, v0
	v_mov_b32_e32 v12, v0
	v_mov_b32_e32 v13, v0
	v_mov_b32_e32 v14, v0
	v_mov_b32_e32 v15, v0
	v_mov_b32_e32 v24, v0
	v_mov_b32_e32 v25, v0
	v_mov_b32_e32 v26, v0
	v_mov_b32_e32 v27, v0
	v_mov_b32_e32 v28, v0
	v_mov_b32_e32 v29, v0
	v_mov_b32_e32 v30, v0
	v_mov_b32_e32 v31, v0
	v_mov_b32_e32 v40, v0
	v_mov_b32_e32 v41, v0
	v_mov_b32_e32 v42, v0
	v_mov_b32_e32 v43, v0
	v_mov_b32_e32 v44, v0
	v_mov_b32_e32 v45, v0
	v_mov_b32_e32 v46, v0
	v_mov_b32_e32 v47, v0
	v_mov_b32_e32 v56, v0
	v_mov_b32_e32 v57, v0
	v_mov_b32_e32 v58, v0
	v_mov_b32_e32 v59, v0
	v_mov_b32_e32 v60, v0
	v_mov_b32_e32 v61, v0
	v_mov_b32_e32 v62, v0
	v_mov_b32_e32 v63, v0
	v_mov_b32_e32 v64, v0
	v_mov_b32_e32 v65, v0
	v_mov_b32_e32 v66, v0
	v_mov_b32_e32 v67, v0
	v_mov_b32_e32 v68, v0
	v_mov_b32_e32 v69, v0
	v_mov_b32_e32 v70, v0
	v_mov_b32_e32 v71, v0
	v_mov_b32_e32 v80, v0
	v_mov_b32_e32 v81, v0
	v_mov_b32_e32 v82, v0
	v_mov_b32_e32 v83, v0
	v_mov_b32_e32 v84, v0
	v_mov_b32_e32 v85, v0
	v_mov_b32_e32 v86, v0
	v_mov_b32_e32 v87, v0
	v_mov_b32_e32 v96, v0
	v_mov_b32_e32 v97, v0
	v_mov_b32_e32 v98, v0
	v_mov_b32_e32 v99, v0
	v_mov_b32_e32 v100, v0
	v_mov_b32_e32 v101, v0
	v_mov_b32_e32 v102, v0
	v_mov_b32_e32 v103, v0
	v_mov_b32_e32 v112, v0
	v_mov_b32_e32 v113, v0
	v_mov_b32_e32 v114, v0
	v_mov_b32_e32 v115, v0
	v_mov_b32_e32 v116, v0
	v_mov_b32_e32 v117, v0
	v_mov_b32_e32 v118, v0
	v_mov_b32_e32 v119, v0
	v_mov_b32_e32 v72, v0
	v_mov_b32_e32 v73, v0
	v_mov_b32_e32 v74, v0
	v_mov_b32_e32 v75, v0
	v_mov_b32_e32 v76, v0
	v_mov_b32_e32 v77, v0
	v_mov_b32_e32 v78, v0
	v_mov_b32_e32 v79, v0
	v_mov_b32_e32 v88, v0
	v_mov_b32_e32 v89, v0
	v_mov_b32_e32 v90, v0
	v_mov_b32_e32 v91, v0
	v_mov_b32_e32 v92, v0
	v_mov_b32_e32 v93, v0
	v_mov_b32_e32 v94, v0
	v_mov_b32_e32 v95, v0
	v_mov_b32_e32 v104, v0
	v_mov_b32_e32 v105, v0
	v_mov_b32_e32 v106, v0
	v_mov_b32_e32 v107, v0
	v_mov_b32_e32 v108, v0
	v_mov_b32_e32 v109, v0
	v_mov_b32_e32 v110, v0
	v_mov_b32_e32 v111, v0
	v_mov_b32_e32 v120, v0
	v_mov_b32_e32 v121, v0
	v_mov_b32_e32 v122, v0
	v_mov_b32_e32 v123, v0
	v_mov_b32_e32 v124, v0
	v_mov_b32_e32 v125, v0
	v_mov_b32_e32 v126, v0
	v_mov_b32_e32 v127, v0
	s_cmp_lg_u32 s71, 0
	s_cbranch_scc1 .Lhalf_sel_B

.Lhalf_sel_B:
	s_cmp_eq_u32 s71, 1
	s_cbranch_scc1 .Lh0_B_160
	s_branch .Lh1_B_160
.Lh0_B_160:
	s_add_u32 s20, s18, 0xfffc0080
	s_addc_u32 s21, s19, -1
	s_add_i32 s45, 0, 0x10000
	s_cmp_eq_u32 s44, 12
	s_cselect_b32 s23, s13, s21
	s_cselect_b32 s22, s40, s20
	v_add_u32_e32 v134, s45, v151
	s_cselect_b32 s21, s11, s43
	s_cselect_b32 s20, s41, s42
	s_add_i32 s48, 0, 0x14000
	ds_read_b128 v[154:157], v134
	ds_read_b128 v[176:179], v134 offset:1024
	ds_read_b128 v[190:193], v134 offset:2048
	ds_read_b128 v[194:197], v134 offset:3072
	v_add_u32_e32 v134, s48, v151
	v_lshl_add_u64 v[134:135], s[18:19], 0, v[144:145]
	s_add_i32 m0, s27, 0xc000
	ds_read_b128 v[214:217], v153
	ds_read_b128 v[218:221], v153 offset:1024
	ds_read_b128 v[222:225], v153 offset:2048
	ds_read_b128 v[226:229], v153 offset:3072
	ds_read_b128 v[230:233], v153 offset:4096
	ds_read_b128 v[234:237], v153 offset:5120
	ds_read_b128 v[238:241], v153 offset:6144
	ds_read_b128 v[242:245], v153 offset:7168
	global_load_lds_dwordx4 v[134:135], off
	v_lshl_add_u64 v[134:135], s[18:19], 0, v[146:147]
	s_add_i32 m0, s27, 0xe000
	s_nop 0
	global_load_lds_dwordx4 v[134:135], off
	s_waitcnt vmcnt(6)
	s_waitcnt lgkmcnt(0)
	s_barrier
	s_setprio 1
	s_waitcnt lgkmcnt(0)
	v_mfma_f32_16x16x32_bf16 v[124:127], v[154:157], v[214:217], v[124:127]
	v_mfma_f32_16x16x32_bf16 v[120:123], v[190:193], v[214:217], v[120:123]
	v_mfma_f32_16x16x32_bf16 v[108:111], v[154:157], v[222:225], v[108:111]
	v_mfma_f32_16x16x32_bf16 v[104:107], v[190:193], v[222:225], v[104:107]
	v_mfma_f32_16x16x32_bf16 v[92:95], v[154:157], v[230:233], v[92:95]
	v_mfma_f32_16x16x32_bf16 v[88:91], v[190:193], v[230:233], v[88:91]
	v_mfma_f32_16x16x32_bf16 v[76:79], v[154:157], v[238:241], v[76:79]
	v_mfma_f32_16x16x32_bf16 v[72:75], v[190:193], v[238:241], v[72:75]
	v_mfma_f32_16x16x32_bf16 v[124:127], v[176:179], v[218:221], v[124:127]
	v_mfma_f32_16x16x32_bf16 v[120:123], v[194:197], v[218:221], v[120:123]
	v_mfma_f32_16x16x32_bf16 v[108:111], v[176:179], v[226:229], v[108:111]
	v_mfma_f32_16x16x32_bf16 v[104:107], v[194:197], v[226:229], v[104:107]
	v_mfma_f32_16x16x32_bf16 v[92:95], v[176:179], v[234:237], v[92:95]
	v_mfma_f32_16x16x32_bf16 v[88:91], v[194:197], v[234:237], v[88:91]
	v_mfma_f32_16x16x32_bf16 v[76:79], v[176:179], v[242:245], v[76:79]
	v_mfma_f32_16x16x32_bf16 v[72:75], v[194:197], v[242:245], v[72:75]
	s_setprio 0
	s_setprio 1
	s_setprio 0
	s_barrier
	s_add_i32 s45, s45, s26
	v_lshl_add_u64 v[134:135], s[20:21], 0, v[128:129]
	s_mov_b32 m0, s45
	ds_read_b128 v[214:217], v153 offset:16384
	ds_read_b128 v[218:221], v153 offset:17408
	ds_read_b128 v[222:225], v153 offset:18432
	ds_read_b128 v[226:229], v153 offset:19456
	ds_read_b128 v[230:233], v153 offset:20480
	ds_read_b128 v[234:237], v153 offset:21504
	ds_read_b128 v[238:241], v153 offset:22528
	ds_read_b128 v[242:245], v153 offset:23552
	global_load_lds_dwordx4 v[134:135], off
	s_add_i32 m0, s45, 0x2000
	s_add_u32 s46, s20, 0x40000
	v_lshl_add_u64 v[136:137], s[20:21], 0, v[138:139]
	s_addc_u32 s47, s21, 0
	s_add_i32 s45, s48, s26
	global_load_lds_dwordx4 v[136:137], off
	v_lshl_add_u64 v[148:149], s[46:47], 0, v[128:129]
	s_mov_b32 m0, s45
	v_lshl_add_u64 v[158:159], s[22:23], 0, v[140:141]
	v_lshl_add_u64 v[148:149], s[46:47], 0, v[138:139]
	s_add_i32 m0, s45, 0x2000
	s_nop 0
	v_lshl_add_u64 v[148:149], s[22:23], 0, v[142:143]
	s_mov_b32 m0, s27
	s_nop 0
	global_load_lds_dwordx4 v[148:149], off
	s_mov_b32 m0, s29
	s_nop 0
	global_load_lds_dwordx4 v[158:159], off
	s_waitcnt vmcnt(6)
	s_waitcnt lgkmcnt(0)
	s_barrier
	s_setprio 1
	s_waitcnt lgkmcnt(0)
	v_mfma_f32_16x16x32_bf16 v[60:63], v[154:157], v[214:217], v[60:63]
	v_mfma_f32_16x16x32_bf16 v[56:59], v[190:193], v[214:217], v[56:59]
	v_mfma_f32_16x16x32_bf16 v[44:47], v[154:157], v[222:225], v[44:47]
	v_mfma_f32_16x16x32_bf16 v[40:43], v[190:193], v[222:225], v[40:43]
	v_mfma_f32_16x16x32_bf16 v[28:31], v[154:157], v[230:233], v[28:31]
	v_mfma_f32_16x16x32_bf16 v[24:27], v[190:193], v[230:233], v[24:27]
	v_mfma_f32_16x16x32_bf16 v[12:15], v[154:157], v[238:241], v[12:15]
	v_mfma_f32_16x16x32_bf16 v[8:11], v[190:193], v[238:241], v[8:11]
	v_mfma_f32_16x16x32_bf16 v[60:63], v[176:179], v[218:221], v[60:63]
	v_mfma_f32_16x16x32_bf16 v[56:59], v[194:197], v[218:221], v[56:59]
	v_mfma_f32_16x16x32_bf16 v[44:47], v[176:179], v[226:229], v[44:47]
	v_mfma_f32_16x16x32_bf16 v[40:43], v[194:197], v[226:229], v[40:43]
	v_mfma_f32_16x16x32_bf16 v[28:31], v[176:179], v[234:237], v[28:31]
	v_mfma_f32_16x16x32_bf16 v[24:27], v[194:197], v[234:237], v[24:27]
	v_mfma_f32_16x16x32_bf16 v[12:15], v[176:179], v[242:245], v[12:15]
	v_mfma_f32_16x16x32_bf16 v[8:11], v[194:197], v[242:245], v[8:11]
	s_setprio 0
	s_setprio 1
	s_setprio 0
	s_barrier
	s_add_i32 s45, 0, 0x18000
	v_add_u32_e32 v180, s45, v151
	s_add_i32 s46, 0, 0x1c000
	ds_read_b128 v[154:157], v180
	ds_read_b128 v[176:179], v180 offset:1024
	ds_read_b128 v[190:193], v180 offset:2048
	ds_read_b128 v[194:197], v180 offset:3072
	v_add_u32_e32 v180, s46, v151
	s_add_u32 s22, s22, 0x40000
	s_addc_u32 s23, s23, 0
	s_mov_b32 m0, s30
	v_lshl_add_u64 v[180:181], s[22:23], 0, v[142:143]
	ds_read_b128 v[214:217], v153 offset:32768
	ds_read_b128 v[218:221], v153 offset:33792
	ds_read_b128 v[222:225], v153 offset:34816
	ds_read_b128 v[226:229], v153 offset:35840
	ds_read_b128 v[230:233], v153 offset:36864
	ds_read_b128 v[234:237], v153 offset:37888
	ds_read_b128 v[238:241], v153 offset:38912
	ds_read_b128 v[242:245], v153 offset:39936
	global_load_lds_dwordx4 v[180:181], off
	v_lshl_add_u64 v[180:181], s[22:23], 0, v[140:141]
	s_mov_b32 m0, s31
	s_nop 0
	global_load_lds_dwordx4 v[180:181], off
	s_waitcnt vmcnt(6)
	s_waitcnt lgkmcnt(0)
	s_barrier
	s_setprio 1
	s_waitcnt lgkmcnt(0)
	v_mfma_f32_16x16x32_bf16 v[124:127], v[154:157], v[214:217], v[124:127]
	v_mfma_f32_16x16x32_bf16 v[120:123], v[190:193], v[214:217], v[120:123]
	v_mfma_f32_16x16x32_bf16 v[108:111], v[154:157], v[222:225], v[108:111]
	v_mfma_f32_16x16x32_bf16 v[104:107], v[190:193], v[222:225], v[104:107]
	v_mfma_f32_16x16x32_bf16 v[92:95], v[154:157], v[230:233], v[92:95]
	v_mfma_f32_16x16x32_bf16 v[88:91], v[190:193], v[230:233], v[88:91]
	v_mfma_f32_16x16x32_bf16 v[76:79], v[154:157], v[238:241], v[76:79]
	v_mfma_f32_16x16x32_bf16 v[72:75], v[190:193], v[238:241], v[72:75]
	v_mfma_f32_16x16x32_bf16 v[124:127], v[176:179], v[218:221], v[124:127]
	v_mfma_f32_16x16x32_bf16 v[120:123], v[194:197], v[218:221], v[120:123]
	v_mfma_f32_16x16x32_bf16 v[108:111], v[176:179], v[226:229], v[108:111]
	v_mfma_f32_16x16x32_bf16 v[104:107], v[194:197], v[226:229], v[104:107]
	v_mfma_f32_16x16x32_bf16 v[92:95], v[176:179], v[234:237], v[92:95]
	v_mfma_f32_16x16x32_bf16 v[88:91], v[194:197], v[234:237], v[88:91]
	v_mfma_f32_16x16x32_bf16 v[76:79], v[176:179], v[242:245], v[76:79]
	v_mfma_f32_16x16x32_bf16 v[72:75], v[194:197], v[242:245], v[72:75]
	s_setprio 0
	s_setprio 1
	s_setprio 0
	s_barrier
	s_add_i32 s22, s45, s26
	v_lshl_add_u64 v[134:135], v[134:135], 0, s[2:3]
	s_mov_b32 m0, s22
	ds_read_b128 v[214:217], v153 offset:49152
	ds_read_b128 v[218:221], v153 offset:50176
	ds_read_b128 v[222:225], v153 offset:51200
	ds_read_b128 v[226:229], v153 offset:52224
	ds_read_b128 v[230:233], v153 offset:53248
	ds_read_b128 v[234:237], v153 offset:54272
	ds_read_b128 v[238:241], v153 offset:55296
	ds_read_b128 v[242:245], v153 offset:56320
	global_load_lds_dwordx4 v[134:135], off
	s_add_i32 m0, s22, 0x2000
	s_add_u32 s20, s20, 0x40080
	v_lshl_add_u64 v[134:135], v[136:137], 0, s[2:3]
	s_addc_u32 s21, s21, 0
	s_add_i32 s22, s46, s26
	global_load_lds_dwordx4 v[134:135], off
	v_lshl_add_u64 v[134:135], s[20:21], 0, v[128:129]
	s_mov_b32 m0, s22
	s_nop 0
	v_lshl_add_u64 v[134:135], s[20:21], 0, v[138:139]
	s_add_i32 m0, s22, 0x2000
	s_nop 0
	v_lshl_add_u64 v[134:135], v[148:149], 0, s[2:3]
	s_mov_b32 m0, s34
	s_nop 0
	global_load_lds_dwordx4 v[134:135], off
	v_lshl_add_u64 v[134:135], v[158:159], 0, s[2:3]
	s_mov_b32 m0, s35
	s_nop 0
	global_load_lds_dwordx4 v[134:135], off
	s_waitcnt vmcnt(6)
	s_waitcnt lgkmcnt(0)
	s_barrier
	s_setprio 1
	s_waitcnt lgkmcnt(0)
	v_mfma_f32_16x16x32_bf16 v[60:63], v[154:157], v[214:217], v[60:63]
	v_mfma_f32_16x16x32_bf16 v[56:59], v[190:193], v[214:217], v[56:59]
	v_mfma_f32_16x16x32_bf16 v[44:47], v[154:157], v[222:225], v[44:47]
	v_mfma_f32_16x16x32_bf16 v[40:43], v[190:193], v[222:225], v[40:43]
	v_mfma_f32_16x16x32_bf16 v[28:31], v[154:157], v[230:233], v[28:31]
	v_mfma_f32_16x16x32_bf16 v[24:27], v[190:193], v[230:233], v[24:27]
	v_mfma_f32_16x16x32_bf16 v[12:15], v[154:157], v[238:241], v[12:15]
	v_mfma_f32_16x16x32_bf16 v[8:11], v[190:193], v[238:241], v[8:11]
	v_mfma_f32_16x16x32_bf16 v[60:63], v[176:179], v[218:221], v[60:63]
	v_mfma_f32_16x16x32_bf16 v[56:59], v[194:197], v[218:221], v[56:59]
	v_mfma_f32_16x16x32_bf16 v[44:47], v[176:179], v[226:229], v[44:47]
	v_mfma_f32_16x16x32_bf16 v[40:43], v[194:197], v[226:229], v[40:43]
	v_mfma_f32_16x16x32_bf16 v[28:31], v[176:179], v[234:237], v[28:31]
	v_mfma_f32_16x16x32_bf16 v[24:27], v[194:197], v[234:237], v[24:27]
	v_mfma_f32_16x16x32_bf16 v[12:15], v[176:179], v[242:245], v[12:15]
	v_mfma_f32_16x16x32_bf16 v[8:11], v[194:197], v[242:245], v[8:11]
	s_setprio 0
	s_setprio 1
	s_setprio 0
	s_barrier
	s_add_i32 s44, s44, 2
	s_add_u32 s18, s18, 0x100
	s_addc_u32 s19, s19, 0
	s_add_u32 s42, s42, 0x100
	s_addc_u32 s43, s43, 0
	s_cmp_gt_u32 s44, 13
	s_cbranch_scc0 .Lh0_B_160
	s_and_b64 vcc, exec, s[6:7]
	s_cbranch_vccz .Lh0_B_163
	s_barrier
.Lh0_B_163:
	v_lshl_add_u32 v148, s39, 8, v150
	v_max_f32_e32 v124, v124, v124
	v_max_f32_e32 v120, v120, v120
	v_max_f32_e32 v125, v125, v125
	v_max_f32_e32 v121, v121, v121
	v_max_f32_e32 v126, v126, v126
	v_max_f32_e32 v127, v127, v127
	v_lshl_or_b32 v134, s38, 8, v152
	v_ashrrev_i32_e32 v149, 31, v148
	v_max_f32_e32 v124, 0, v124
	v_max_f32_e32 v120, 0, v120
	v_max_f32_e32 v125, 0, v125
	v_max_f32_e32 v121, 0, v121
	v_max_f32_e32 v126, 0, v126
	v_max_f32_e32 v122, v122, v122
	v_max_f32_e32 v127, 0, v127
	v_max_f32_e32 v123, v123, v123
	v_lshlrev_b64 v[136:137], 13, v[148:149]
	v_pk_mul_f32 v[124:125], v[124:125], v[124:125]
	v_pk_mul_f32 v[120:121], v[120:121], v[120:121]
	v_max_f32_e32 v122, 0, v122
	v_max_f32_e32 v123, 0, v123
	v_pk_mul_f32 v[126:127], v[126:127], v[126:127]
	v_ashrrev_i32_e32 v135, 31, v134
	v_pk_mul_f32 v[154:155], v[122:123], v[122:123]
	v_cvt_pk_bf16_f32 v122, v124, v125
	v_cvt_pk_bf16_f32 v123, v126, v127
	v_cvt_pk_bf16_f32 v124, v120, v121
	v_lshl_add_u64 v[126:127], s[8:9], 0, v[136:137]
	v_lshlrev_b64 v[120:121], 1, v[134:135]
	v_max_f32_e32 v112, v112, v112
	v_max_f32_e32 v113, v113, v113
	v_cvt_pk_bf16_f32 v125, v154, v155
	v_lshl_add_u64 v[126:127], v[126:127], 0, v[120:121]
	v_max_f32_e32 v112, 0, v112
	v_max_f32_e32 v113, 0, v113
	global_store_dwordx4 v[126:127], v[122:125], off
	v_max_f32_e32 v116, v116, v116
	v_max_f32_e32 v117, v117, v117
	v_pk_mul_f32 v[122:123], v[112:113], v[112:113]
	v_max_f32_e32 v113, v114, v114
	v_max_f32_e32 v112, v118, v118
	v_max_f32_e32 v114, 0, v113
	v_max_f32_e32 v113, v119, v119
	v_max_f32_e32 v115, v115, v115
	v_max_f32_e32 v116, 0, v116
	v_max_f32_e32 v117, 0, v117
	v_max_f32_e32 v112, 0, v112
	v_max_f32_e32 v113, 0, v113
	v_max_f32_e32 v115, 0, v115
	v_pk_mul_f32 v[116:117], v[116:117], v[116:117]
	v_pk_mul_f32 v[118:119], v[112:113], v[112:113]
	v_pk_mul_f32 v[124:125], v[114:115], v[114:115]
	v_max_f32_e32 v104, v104, v104
	v_max_f32_e32 v105, v105, v105
	v_cvt_pk_bf16_f32 v112, v116, v117
	v_cvt_pk_bf16_f32 v113, v118, v119
	v_cvt_pk_bf16_f32 v114, v122, v123
	v_cvt_pk_bf16_f32 v115, v124, v125
	v_max_f32_e32 v104, 0, v104
	v_max_f32_e32 v105, 0, v105
	v_max_f32_e32 v108, v108, v108
	v_max_f32_e32 v109, v109, v109
	v_or_b32_e32 v112, 16, v148
	v_pk_mul_f32 v[114:115], v[104:105], v[104:105]
	v_max_f32_e32 v105, v106, v106
	v_ashrrev_i32_e32 v113, 31, v112
	v_max_f32_e32 v108, 0, v108
	v_max_f32_e32 v109, 0, v109
	v_max_f32_e32 v104, v110, v110
	v_max_f32_e32 v106, 0, v105
	v_max_f32_e32 v105, v111, v111
	v_max_f32_e32 v107, v107, v107
	v_lshlrev_b64 v[112:113], 13, v[112:113]
	v_pk_mul_f32 v[108:109], v[108:109], v[108:109]
	v_max_f32_e32 v104, 0, v104
	v_max_f32_e32 v105, 0, v105
	v_max_f32_e32 v107, 0, v107
	v_pk_mul_f32 v[110:111], v[104:105], v[104:105]
	v_pk_mul_f32 v[116:117], v[106:107], v[106:107]
	v_cvt_pk_bf16_f32 v104, v108, v109
	v_lshl_add_u64 v[108:109], s[8:9], 0, v[112:113]
	v_max_f32_e32 v96, v96, v96
	v_max_f32_e32 v97, v97, v97
	v_cvt_pk_bf16_f32 v105, v110, v111
	v_cvt_pk_bf16_f32 v106, v114, v115
	v_cvt_pk_bf16_f32 v107, v116, v117
	v_lshl_add_u64 v[108:109], v[108:109], 0, v[120:121]
	v_max_f32_e32 v96, 0, v96
	v_max_f32_e32 v97, 0, v97
	global_store_dwordx4 v[108:109], v[104:107], off
	v_max_f32_e32 v100, v100, v100
	v_max_f32_e32 v101, v101, v101
	v_pk_mul_f32 v[104:105], v[96:97], v[96:97]
	v_max_f32_e32 v97, v98, v98
	v_max_f32_e32 v96, v102, v102
	v_max_f32_e32 v98, 0, v97
	v_max_f32_e32 v97, v103, v103
	v_max_f32_e32 v99, v99, v99
	v_max_f32_e32 v100, 0, v100
	v_max_f32_e32 v101, 0, v101
	v_max_f32_e32 v96, 0, v96
	v_max_f32_e32 v97, 0, v97
	v_max_f32_e32 v99, 0, v99
	v_pk_mul_f32 v[100:101], v[100:101], v[100:101]
	v_pk_mul_f32 v[102:103], v[96:97], v[96:97]
	v_pk_mul_f32 v[106:107], v[98:99], v[98:99]
	v_max_f32_e32 v88, v88, v88
	v_max_f32_e32 v89, v89, v89
	v_cvt_pk_bf16_f32 v96, v100, v101
	v_cvt_pk_bf16_f32 v97, v102, v103
	v_cvt_pk_bf16_f32 v98, v104, v105
	v_cvt_pk_bf16_f32 v99, v106, v107
	v_max_f32_e32 v88, 0, v88
	v_max_f32_e32 v89, 0, v89
	v_max_f32_e32 v92, v92, v92
	v_max_f32_e32 v93, v93, v93
	v_or_b32_e32 v96, 32, v148
	v_pk_mul_f32 v[98:99], v[88:89], v[88:89]
	v_max_f32_e32 v89, v90, v90
	v_ashrrev_i32_e32 v97, 31, v96
	v_max_f32_e32 v92, 0, v92
	v_max_f32_e32 v93, 0, v93
	v_max_f32_e32 v88, v94, v94
	v_max_f32_e32 v90, 0, v89
	v_max_f32_e32 v89, v95, v95
	v_max_f32_e32 v91, v91, v91
	v_lshlrev_b64 v[96:97], 13, v[96:97]
	v_pk_mul_f32 v[92:93], v[92:93], v[92:93]
	v_max_f32_e32 v88, 0, v88
	v_max_f32_e32 v89, 0, v89
	v_max_f32_e32 v91, 0, v91
	v_pk_mul_f32 v[94:95], v[88:89], v[88:89]
	v_pk_mul_f32 v[100:101], v[90:91], v[90:91]
	v_cvt_pk_bf16_f32 v88, v92, v93
	v_lshl_add_u64 v[92:93], s[8:9], 0, v[96:97]
	v_max_f32_e32 v80, v80, v80
	v_max_f32_e32 v81, v81, v81
	v_cvt_pk_bf16_f32 v89, v94, v95
	v_cvt_pk_bf16_f32 v90, v98, v99
	v_cvt_pk_bf16_f32 v91, v100, v101
	v_lshl_add_u64 v[92:93], v[92:93], 0, v[120:121]
	v_max_f32_e32 v80, 0, v80
	v_max_f32_e32 v81, 0, v81
	global_store_dwordx4 v[92:93], v[88:91], off
	v_max_f32_e32 v84, v84, v84
	v_max_f32_e32 v85, v85, v85
	v_pk_mul_f32 v[88:89], v[80:81], v[80:81]
	v_max_f32_e32 v81, v82, v82
	v_max_f32_e32 v80, v86, v86
	v_max_f32_e32 v82, 0, v81
	v_max_f32_e32 v81, v87, v87
	v_max_f32_e32 v83, v83, v83
	v_max_f32_e32 v84, 0, v84
	v_max_f32_e32 v85, 0, v85
	v_max_f32_e32 v80, 0, v80
	v_max_f32_e32 v81, 0, v81
	v_max_f32_e32 v83, 0, v83
	v_pk_mul_f32 v[84:85], v[84:85], v[84:85]
	v_pk_mul_f32 v[86:87], v[80:81], v[80:81]
	v_pk_mul_f32 v[90:91], v[82:83], v[82:83]
	v_max_f32_e32 v72, v72, v72
	v_max_f32_e32 v73, v73, v73
	v_cvt_pk_bf16_f32 v80, v84, v85
	v_cvt_pk_bf16_f32 v81, v86, v87
	v_cvt_pk_bf16_f32 v82, v88, v89
	v_cvt_pk_bf16_f32 v83, v90, v91
	v_max_f32_e32 v72, 0, v72
	v_max_f32_e32 v73, 0, v73
	v_max_f32_e32 v76, v76, v76
	v_max_f32_e32 v77, v77, v77
	v_or_b32_e32 v80, 48, v148
	v_pk_mul_f32 v[82:83], v[72:73], v[72:73]
	v_max_f32_e32 v73, v74, v74
	v_ashrrev_i32_e32 v81, 31, v80
	v_max_f32_e32 v76, 0, v76
	v_max_f32_e32 v77, 0, v77
	v_max_f32_e32 v72, v78, v78
	v_max_f32_e32 v74, 0, v73
	v_max_f32_e32 v73, v79, v79
	v_max_f32_e32 v75, v75, v75
	v_lshlrev_b64 v[80:81], 13, v[80:81]
	v_pk_mul_f32 v[76:77], v[76:77], v[76:77]
	v_max_f32_e32 v72, 0, v72
	v_max_f32_e32 v73, 0, v73
	v_max_f32_e32 v75, 0, v75
	v_pk_mul_f32 v[78:79], v[72:73], v[72:73]
	v_pk_mul_f32 v[84:85], v[74:75], v[74:75]
	v_cvt_pk_bf16_f32 v72, v76, v77
	v_lshl_add_u64 v[76:77], s[8:9], 0, v[80:81]
	v_max_f32_e32 v64, v64, v64
	v_max_f32_e32 v65, v65, v65
	v_cvt_pk_bf16_f32 v73, v78, v79
	v_cvt_pk_bf16_f32 v74, v82, v83
	v_cvt_pk_bf16_f32 v75, v84, v85
	v_lshl_add_u64 v[76:77], v[76:77], 0, v[120:121]
	v_max_f32_e32 v64, 0, v64
	v_max_f32_e32 v65, 0, v65
	global_store_dwordx4 v[76:77], v[72:75], off
	v_max_f32_e32 v68, v68, v68
	v_max_f32_e32 v69, v69, v69
	v_pk_mul_f32 v[72:73], v[64:65], v[64:65]
	v_max_f32_e32 v65, v66, v66
	v_max_f32_e32 v64, v70, v70
	v_max_f32_e32 v66, 0, v65
	v_max_f32_e32 v65, v71, v71
	v_max_f32_e32 v67, v67, v67
	v_max_f32_e32 v68, 0, v68
	v_max_f32_e32 v69, 0, v69
	v_max_f32_e32 v64, 0, v64
	v_max_f32_e32 v65, 0, v65
	v_max_f32_e32 v67, 0, v67
	v_pk_mul_f32 v[68:69], v[68:69], v[68:69]
	v_pk_mul_f32 v[70:71], v[64:65], v[64:65]
	v_pk_mul_f32 v[74:75], v[66:67], v[66:67]
	v_max_f32_e32 v56, v56, v56
	v_max_f32_e32 v57, v57, v57
	v_cvt_pk_bf16_f32 v64, v68, v69
	v_cvt_pk_bf16_f32 v65, v70, v71
	v_cvt_pk_bf16_f32 v66, v72, v73
	v_cvt_pk_bf16_f32 v67, v74, v75
	v_max_f32_e32 v56, 0, v56
	v_max_f32_e32 v57, 0, v57
	v_max_f32_e32 v60, v60, v60
	v_max_f32_e32 v61, v61, v61
	v_add_u32_e32 v64, 0x80, v148
	v_pk_mul_f32 v[66:67], v[56:57], v[56:57]
	v_max_f32_e32 v57, v58, v58
	v_ashrrev_i32_e32 v65, 31, v64
	v_max_f32_e32 v60, 0, v60
	v_max_f32_e32 v61, 0, v61
	v_max_f32_e32 v56, v62, v62
	v_max_f32_e32 v58, 0, v57
	v_max_f32_e32 v57, v63, v63
	v_max_f32_e32 v59, v59, v59
	v_lshlrev_b64 v[64:65], 13, v[64:65]
	v_pk_mul_f32 v[60:61], v[60:61], v[60:61]
	v_max_f32_e32 v56, 0, v56
	v_max_f32_e32 v57, 0, v57
	v_max_f32_e32 v59, 0, v59
	v_pk_mul_f32 v[62:63], v[56:57], v[56:57]
	v_pk_mul_f32 v[68:69], v[58:59], v[58:59]
	v_cvt_pk_bf16_f32 v56, v60, v61
	v_lshl_add_u64 v[60:61], s[8:9], 0, v[64:65]
	v_max_f32_e32 v48, v48, v48
	v_max_f32_e32 v49, v49, v49
	v_cvt_pk_bf16_f32 v57, v62, v63
	v_cvt_pk_bf16_f32 v58, v66, v67
	v_cvt_pk_bf16_f32 v59, v68, v69
	v_lshl_add_u64 v[60:61], v[60:61], 0, v[120:121]
	v_max_f32_e32 v48, 0, v48
	v_max_f32_e32 v49, 0, v49
	global_store_dwordx4 v[60:61], v[56:59], off
	v_max_f32_e32 v52, v52, v52
	v_max_f32_e32 v53, v53, v53
	v_pk_mul_f32 v[56:57], v[48:49], v[48:49]
	v_max_f32_e32 v49, v50, v50
	v_max_f32_e32 v48, v54, v54
	v_max_f32_e32 v50, 0, v49
	v_max_f32_e32 v49, v55, v55
	v_max_f32_e32 v51, v51, v51
	v_max_f32_e32 v52, 0, v52
	v_max_f32_e32 v53, 0, v53
	v_max_f32_e32 v48, 0, v48
	v_max_f32_e32 v49, 0, v49
	v_max_f32_e32 v51, 0, v51
	v_pk_mul_f32 v[52:53], v[52:53], v[52:53]
	v_pk_mul_f32 v[54:55], v[48:49], v[48:49]
	v_pk_mul_f32 v[58:59], v[50:51], v[50:51]
	v_max_f32_e32 v40, v40, v40
	v_max_f32_e32 v41, v41, v41
	v_cvt_pk_bf16_f32 v48, v52, v53
	v_cvt_pk_bf16_f32 v49, v54, v55
	v_cvt_pk_bf16_f32 v50, v56, v57
	v_cvt_pk_bf16_f32 v51, v58, v59
	v_max_f32_e32 v40, 0, v40
	v_max_f32_e32 v41, 0, v41
	v_max_f32_e32 v44, v44, v44
	v_max_f32_e32 v45, v45, v45
	v_add_u32_e32 v48, 0x90, v148
	v_pk_mul_f32 v[50:51], v[40:41], v[40:41]
	v_max_f32_e32 v41, v42, v42
	v_ashrrev_i32_e32 v49, 31, v48
	v_max_f32_e32 v44, 0, v44
	v_max_f32_e32 v45, 0, v45
	v_max_f32_e32 v40, v46, v46
	v_max_f32_e32 v42, 0, v41
	v_max_f32_e32 v41, v47, v47
	v_max_f32_e32 v43, v43, v43
	v_lshlrev_b64 v[48:49], 13, v[48:49]
	v_pk_mul_f32 v[44:45], v[44:45], v[44:45]
	v_max_f32_e32 v40, 0, v40
	v_max_f32_e32 v41, 0, v41
	v_max_f32_e32 v43, 0, v43
	v_pk_mul_f32 v[46:47], v[40:41], v[40:41]
	v_pk_mul_f32 v[52:53], v[42:43], v[42:43]
	v_cvt_pk_bf16_f32 v40, v44, v45
	v_lshl_add_u64 v[44:45], s[8:9], 0, v[48:49]
	v_max_f32_e32 v32, v32, v32
	v_max_f32_e32 v33, v33, v33
	v_cvt_pk_bf16_f32 v41, v46, v47
	v_cvt_pk_bf16_f32 v42, v50, v51
	v_cvt_pk_bf16_f32 v43, v52, v53
	v_lshl_add_u64 v[44:45], v[44:45], 0, v[120:121]
	v_max_f32_e32 v32, 0, v32
	v_max_f32_e32 v33, 0, v33
	global_store_dwordx4 v[44:45], v[40:43], off
	v_max_f32_e32 v36, v36, v36
	v_max_f32_e32 v37, v37, v37
	v_pk_mul_f32 v[40:41], v[32:33], v[32:33]
	v_max_f32_e32 v33, v34, v34
	v_max_f32_e32 v32, v38, v38
	v_max_f32_e32 v34, 0, v33
	v_max_f32_e32 v33, v39, v39
	v_max_f32_e32 v35, v35, v35
	v_max_f32_e32 v36, 0, v36
	v_max_f32_e32 v37, 0, v37
	v_max_f32_e32 v32, 0, v32
	v_max_f32_e32 v33, 0, v33
	v_max_f32_e32 v35, 0, v35
	v_pk_mul_f32 v[36:37], v[36:37], v[36:37]
	v_pk_mul_f32 v[38:39], v[32:33], v[32:33]
	v_pk_mul_f32 v[42:43], v[34:35], v[34:35]
	v_max_f32_e32 v24, v24, v24
	v_max_f32_e32 v25, v25, v25
	v_cvt_pk_bf16_f32 v32, v36, v37
	v_cvt_pk_bf16_f32 v33, v38, v39
	v_cvt_pk_bf16_f32 v34, v40, v41
	v_cvt_pk_bf16_f32 v35, v42, v43
	v_max_f32_e32 v24, 0, v24
	v_max_f32_e32 v25, 0, v25
	v_max_f32_e32 v28, v28, v28
	v_max_f32_e32 v29, v29, v29
	v_add_u32_e32 v32, 0xa0, v148
	v_pk_mul_f32 v[34:35], v[24:25], v[24:25]
	v_max_f32_e32 v25, v26, v26
	v_ashrrev_i32_e32 v33, 31, v32
	v_max_f32_e32 v28, 0, v28
	v_max_f32_e32 v29, 0, v29
	v_max_f32_e32 v24, v30, v30
	v_max_f32_e32 v26, 0, v25
	v_max_f32_e32 v25, v31, v31
	v_max_f32_e32 v27, v27, v27
	v_lshlrev_b64 v[32:33], 13, v[32:33]
	v_pk_mul_f32 v[28:29], v[28:29], v[28:29]
	v_max_f32_e32 v24, 0, v24
	v_max_f32_e32 v25, 0, v25
	v_max_f32_e32 v27, 0, v27
	v_pk_mul_f32 v[30:31], v[24:25], v[24:25]
	v_pk_mul_f32 v[36:37], v[26:27], v[26:27]
	v_cvt_pk_bf16_f32 v24, v28, v29
	v_lshl_add_u64 v[28:29], s[8:9], 0, v[32:33]
	v_max_f32_e32 v16, v16, v16
	v_max_f32_e32 v17, v17, v17
	v_cvt_pk_bf16_f32 v25, v30, v31
	v_cvt_pk_bf16_f32 v26, v34, v35
	v_cvt_pk_bf16_f32 v27, v36, v37
	v_lshl_add_u64 v[28:29], v[28:29], 0, v[120:121]
	v_max_f32_e32 v16, 0, v16
	v_max_f32_e32 v17, 0, v17
	global_store_dwordx4 v[28:29], v[24:27], off
	v_max_f32_e32 v20, v20, v20
	v_max_f32_e32 v21, v21, v21
	v_pk_mul_f32 v[24:25], v[16:17], v[16:17]
	v_max_f32_e32 v17, v18, v18
	v_max_f32_e32 v16, v22, v22
	v_max_f32_e32 v18, 0, v17
	v_max_f32_e32 v17, v23, v23
	v_max_f32_e32 v19, v19, v19
	v_max_f32_e32 v20, 0, v20
	v_max_f32_e32 v21, 0, v21
	v_max_f32_e32 v16, 0, v16
	v_max_f32_e32 v17, 0, v17
	v_max_f32_e32 v19, 0, v19
	v_pk_mul_f32 v[20:21], v[20:21], v[20:21]
	v_pk_mul_f32 v[22:23], v[16:17], v[16:17]
	v_pk_mul_f32 v[26:27], v[18:19], v[18:19]
	v_max_f32_e32 v8, v8, v8
	v_max_f32_e32 v9, v9, v9
	v_cvt_pk_bf16_f32 v16, v20, v21
	v_cvt_pk_bf16_f32 v17, v22, v23
	v_cvt_pk_bf16_f32 v18, v24, v25
	v_cvt_pk_bf16_f32 v19, v26, v27
	v_max_f32_e32 v8, 0, v8
	v_max_f32_e32 v9, 0, v9
	v_max_f32_e32 v12, v12, v12
	v_max_f32_e32 v13, v13, v13
	v_add_u32_e32 v16, 0xb0, v148
	v_pk_mul_f32 v[18:19], v[8:9], v[8:9]
	v_max_f32_e32 v9, v10, v10
	v_ashrrev_i32_e32 v17, 31, v16
	v_max_f32_e32 v12, 0, v12
	v_max_f32_e32 v13, 0, v13
	v_max_f32_e32 v8, v14, v14
	v_max_f32_e32 v10, 0, v9
	v_max_f32_e32 v9, v15, v15
	v_max_f32_e32 v11, v11, v11
	v_lshlrev_b64 v[16:17], 13, v[16:17]
	v_pk_mul_f32 v[12:13], v[12:13], v[12:13]
	v_max_f32_e32 v8, 0, v8
	v_max_f32_e32 v9, 0, v9
	v_max_f32_e32 v11, 0, v11
	v_pk_mul_f32 v[14:15], v[8:9], v[8:9]
	v_pk_mul_f32 v[20:21], v[10:11], v[10:11]
	v_cvt_pk_bf16_f32 v8, v12, v13
	v_lshl_add_u64 v[12:13], s[8:9], 0, v[16:17]
	v_max_f32_e32 v0, v0, v0
	v_max_f32_e32 v1, v1, v1
	v_cvt_pk_bf16_f32 v9, v14, v15
	v_cvt_pk_bf16_f32 v10, v18, v19
	v_cvt_pk_bf16_f32 v11, v20, v21
	v_lshl_add_u64 v[12:13], v[12:13], 0, v[120:121]
	v_max_f32_e32 v0, 0, v0
	v_max_f32_e32 v1, 0, v1
	global_store_dwordx4 v[12:13], v[8:11], off
	v_max_f32_e32 v4, v4, v4
	v_max_f32_e32 v5, v5, v5
	v_pk_mul_f32 v[8:9], v[0:1], v[0:1]
	v_max_f32_e32 v1, v2, v2
	v_max_f32_e32 v0, v6, v6
	v_max_f32_e32 v2, 0, v1
	v_max_f32_e32 v1, v7, v7
	v_max_f32_e32 v3, v3, v3
	v_max_f32_e32 v4, 0, v4
	v_max_f32_e32 v5, 0, v5
	v_max_f32_e32 v0, 0, v0
	v_max_f32_e32 v1, 0, v1
	v_max_f32_e32 v3, 0, v3
	v_pk_mul_f32 v[4:5], v[4:5], v[4:5]
	v_pk_mul_f32 v[6:7], v[0:1], v[0:1]
	v_pk_mul_f32 v[10:11], v[2:3], v[2:3]
	v_cvt_pk_bf16_f32 v0, v4, v5
	v_cvt_pk_bf16_f32 v1, v6, v7
	v_cvt_pk_bf16_f32 v2, v8, v9
	v_cvt_pk_bf16_f32 v3, v10, v11
	s_andn2_b64 vcc, exec, s[0:1]
	s_mov_b64 s[0:1], -1
	s_movk_i32 s48, 0x90
	s_cbranch_vccnz .LBB0_156
	s_andn2_b64 vcc, exec, s[4:5]
	s_cbranch_vccnz .LBB0_155
	s_barrier
	s_branch .LBB0_155
.Lh1_B_160:
	s_add_u32 s20, s18, 0xfffc0080
	s_addc_u32 s21, s19, -1
	s_add_i32 s45, 0, 0x10000
	s_cmp_eq_u32 s44, 12
	s_cselect_b32 s23, s13, s21
	s_cselect_b32 s22, s40, s20
	v_add_u32_e32 v134, s45, v151
	s_cselect_b32 s21, s11, s43
	s_cselect_b32 s20, s41, s42
	s_add_i32 s48, 0, 0x14000
	v_add_u32_e32 v134, s48, v151
	ds_read_b128 v[198:201], v134
	ds_read_b128 v[202:205], v134 offset:1024
	ds_read_b128 v[206:209], v134 offset:2048
	ds_read_b128 v[210:213], v134 offset:3072
	v_lshl_add_u64 v[134:135], s[18:19], 0, v[144:145]
	s_add_i32 m0, s27, 0xc000
	ds_read_b128 v[214:217], v153
	ds_read_b128 v[218:221], v153 offset:1024
	ds_read_b128 v[222:225], v153 offset:2048
	ds_read_b128 v[226:229], v153 offset:3072
	ds_read_b128 v[230:233], v153 offset:4096
	ds_read_b128 v[234:237], v153 offset:5120
	ds_read_b128 v[238:241], v153 offset:6144
	ds_read_b128 v[242:245], v153 offset:7168
	global_load_lds_dwordx4 v[134:135], off
	v_lshl_add_u64 v[134:135], s[18:19], 0, v[146:147]
	s_add_i32 m0, s27, 0xe000
	s_nop 0
	global_load_lds_dwordx4 v[134:135], off
	s_waitcnt vmcnt(6)
	s_waitcnt lgkmcnt(0)
	s_barrier
	s_setprio 1
	s_waitcnt lgkmcnt(0)
	s_setprio 0
	s_setprio 1
	v_mfma_f32_16x16x32_bf16 v[116:119], v[198:201], v[214:217], v[116:119]
	v_mfma_f32_16x16x32_bf16 v[112:115], v[206:209], v[214:217], v[112:115]
	v_mfma_f32_16x16x32_bf16 v[100:103], v[198:201], v[222:225], v[100:103]
	v_mfma_f32_16x16x32_bf16 v[96:99], v[206:209], v[222:225], v[96:99]
	v_mfma_f32_16x16x32_bf16 v[84:87], v[198:201], v[230:233], v[84:87]
	v_mfma_f32_16x16x32_bf16 v[80:83], v[206:209], v[230:233], v[80:83]
	v_mfma_f32_16x16x32_bf16 v[68:71], v[198:201], v[238:241], v[68:71]
	v_mfma_f32_16x16x32_bf16 v[64:67], v[206:209], v[238:241], v[64:67]
	v_mfma_f32_16x16x32_bf16 v[116:119], v[202:205], v[218:221], v[116:119]
	v_mfma_f32_16x16x32_bf16 v[112:115], v[210:213], v[218:221], v[112:115]
	v_mfma_f32_16x16x32_bf16 v[100:103], v[202:205], v[226:229], v[100:103]
	v_mfma_f32_16x16x32_bf16 v[96:99], v[210:213], v[226:229], v[96:99]
	v_mfma_f32_16x16x32_bf16 v[84:87], v[202:205], v[234:237], v[84:87]
	v_mfma_f32_16x16x32_bf16 v[80:83], v[210:213], v[234:237], v[80:83]
	v_mfma_f32_16x16x32_bf16 v[68:71], v[202:205], v[242:245], v[68:71]
	v_mfma_f32_16x16x32_bf16 v[64:67], v[210:213], v[242:245], v[64:67]
	s_setprio 0
	s_barrier
	s_add_i32 s45, s45, s26
	v_lshl_add_u64 v[134:135], s[20:21], 0, v[128:129]
	s_mov_b32 m0, s45
	ds_read_b128 v[214:217], v153 offset:16384
	ds_read_b128 v[218:221], v153 offset:17408
	ds_read_b128 v[222:225], v153 offset:18432
	ds_read_b128 v[226:229], v153 offset:19456
	ds_read_b128 v[230:233], v153 offset:20480
	ds_read_b128 v[234:237], v153 offset:21504
	ds_read_b128 v[238:241], v153 offset:22528
	ds_read_b128 v[242:245], v153 offset:23552
	s_add_i32 m0, s45, 0x2000
	s_add_u32 s46, s20, 0x40000
	v_lshl_add_u64 v[136:137], s[20:21], 0, v[138:139]
	s_addc_u32 s47, s21, 0
	s_add_i32 s45, s48, s26
	v_lshl_add_u64 v[148:149], s[46:47], 0, v[128:129]
	s_mov_b32 m0, s45
	v_lshl_add_u64 v[158:159], s[22:23], 0, v[140:141]
	global_load_lds_dwordx4 v[148:149], off
	v_lshl_add_u64 v[148:149], s[46:47], 0, v[138:139]
	s_add_i32 m0, s45, 0x2000
	s_nop 0
	global_load_lds_dwordx4 v[148:149], off
	v_lshl_add_u64 v[148:149], s[22:23], 0, v[142:143]
	s_mov_b32 m0, s27
	s_nop 0
	global_load_lds_dwordx4 v[148:149], off
	s_mov_b32 m0, s29
	s_nop 0
	global_load_lds_dwordx4 v[158:159], off
	s_waitcnt vmcnt(6)
	s_waitcnt lgkmcnt(0)
	s_barrier
	s_setprio 1
	s_waitcnt lgkmcnt(0)
	s_setprio 0
	s_setprio 1
	v_mfma_f32_16x16x32_bf16 v[52:55], v[198:201], v[214:217], v[52:55]
	v_mfma_f32_16x16x32_bf16 v[48:51], v[206:209], v[214:217], v[48:51]
	v_mfma_f32_16x16x32_bf16 v[36:39], v[198:201], v[222:225], v[36:39]
	v_mfma_f32_16x16x32_bf16 v[32:35], v[206:209], v[222:225], v[32:35]
	v_mfma_f32_16x16x32_bf16 v[20:23], v[198:201], v[230:233], v[20:23]
	v_mfma_f32_16x16x32_bf16 v[16:19], v[206:209], v[230:233], v[16:19]
	v_mfma_f32_16x16x32_bf16 v[4:7], v[198:201], v[238:241], v[4:7]
	v_mfma_f32_16x16x32_bf16 v[0:3], v[206:209], v[238:241], v[0:3]
	v_mfma_f32_16x16x32_bf16 v[52:55], v[202:205], v[218:221], v[52:55]
	v_mfma_f32_16x16x32_bf16 v[48:51], v[210:213], v[218:221], v[48:51]
	v_mfma_f32_16x16x32_bf16 v[36:39], v[202:205], v[226:229], v[36:39]
	v_mfma_f32_16x16x32_bf16 v[32:35], v[210:213], v[226:229], v[32:35]
	v_mfma_f32_16x16x32_bf16 v[20:23], v[202:205], v[234:237], v[20:23]
	v_mfma_f32_16x16x32_bf16 v[16:19], v[210:213], v[234:237], v[16:19]
	v_mfma_f32_16x16x32_bf16 v[4:7], v[202:205], v[242:245], v[4:7]
	v_mfma_f32_16x16x32_bf16 v[0:3], v[210:213], v[242:245], v[0:3]
	s_setprio 0
	s_barrier
	s_add_i32 s45, 0, 0x18000
	v_add_u32_e32 v180, s45, v151
	s_add_i32 s46, 0, 0x1c000
	v_add_u32_e32 v180, s46, v151
	ds_read_b128 v[198:201], v180
	ds_read_b128 v[202:205], v180 offset:1024
	ds_read_b128 v[206:209], v180 offset:2048
	ds_read_b128 v[210:213], v180 offset:3072
	s_add_u32 s22, s22, 0x40000
	s_addc_u32 s23, s23, 0
	s_mov_b32 m0, s30
	v_lshl_add_u64 v[180:181], s[22:23], 0, v[142:143]
	ds_read_b128 v[214:217], v153 offset:32768
	ds_read_b128 v[218:221], v153 offset:33792
	ds_read_b128 v[222:225], v153 offset:34816
	ds_read_b128 v[226:229], v153 offset:35840
	ds_read_b128 v[230:233], v153 offset:36864
	ds_read_b128 v[234:237], v153 offset:37888
	ds_read_b128 v[238:241], v153 offset:38912
	ds_read_b128 v[242:245], v153 offset:39936
	global_load_lds_dwordx4 v[180:181], off
	v_lshl_add_u64 v[180:181], s[22:23], 0, v[140:141]
	s_mov_b32 m0, s31
	s_nop 0
	global_load_lds_dwordx4 v[180:181], off
	s_waitcnt vmcnt(6)
	s_waitcnt lgkmcnt(0)
	s_barrier
	s_setprio 1
	s_waitcnt lgkmcnt(0)
	s_setprio 0
	s_setprio 1
	v_mfma_f32_16x16x32_bf16 v[116:119], v[198:201], v[214:217], v[116:119]
	v_mfma_f32_16x16x32_bf16 v[112:115], v[206:209], v[214:217], v[112:115]
	v_mfma_f32_16x16x32_bf16 v[100:103], v[198:201], v[222:225], v[100:103]
	v_mfma_f32_16x16x32_bf16 v[96:99], v[206:209], v[222:225], v[96:99]
	v_mfma_f32_16x16x32_bf16 v[84:87], v[198:201], v[230:233], v[84:87]
	v_mfma_f32_16x16x32_bf16 v[80:83], v[206:209], v[230:233], v[80:83]
	v_mfma_f32_16x16x32_bf16 v[68:71], v[198:201], v[238:241], v[68:71]
	v_mfma_f32_16x16x32_bf16 v[64:67], v[206:209], v[238:241], v[64:67]
	v_mfma_f32_16x16x32_bf16 v[116:119], v[202:205], v[218:221], v[116:119]
	v_mfma_f32_16x16x32_bf16 v[112:115], v[210:213], v[218:221], v[112:115]
	v_mfma_f32_16x16x32_bf16 v[100:103], v[202:205], v[226:229], v[100:103]
	v_mfma_f32_16x16x32_bf16 v[96:99], v[210:213], v[226:229], v[96:99]
	v_mfma_f32_16x16x32_bf16 v[84:87], v[202:205], v[234:237], v[84:87]
	v_mfma_f32_16x16x32_bf16 v[80:83], v[210:213], v[234:237], v[80:83]
	v_mfma_f32_16x16x32_bf16 v[68:71], v[202:205], v[242:245], v[68:71]
	v_mfma_f32_16x16x32_bf16 v[64:67], v[210:213], v[242:245], v[64:67]
	s_setprio 0
	s_barrier
	s_add_i32 s22, s45, s26
	v_lshl_add_u64 v[134:135], v[134:135], 0, s[2:3]
	s_mov_b32 m0, s22
	ds_read_b128 v[214:217], v153 offset:49152
	ds_read_b128 v[218:221], v153 offset:50176
	ds_read_b128 v[222:225], v153 offset:51200
	ds_read_b128 v[226:229], v153 offset:52224
	ds_read_b128 v[230:233], v153 offset:53248
	ds_read_b128 v[234:237], v153 offset:54272
	ds_read_b128 v[238:241], v153 offset:55296
	ds_read_b128 v[242:245], v153 offset:56320
	s_add_i32 m0, s22, 0x2000
	s_add_u32 s20, s20, 0x40080
	v_lshl_add_u64 v[134:135], v[136:137], 0, s[2:3]
	s_addc_u32 s21, s21, 0
	s_add_i32 s22, s46, s26
	v_lshl_add_u64 v[134:135], s[20:21], 0, v[128:129]
	s_mov_b32 m0, s22
	s_nop 0
	global_load_lds_dwordx4 v[134:135], off
	v_lshl_add_u64 v[134:135], s[20:21], 0, v[138:139]
	s_add_i32 m0, s22, 0x2000
	s_nop 0
	global_load_lds_dwordx4 v[134:135], off
	v_lshl_add_u64 v[134:135], v[148:149], 0, s[2:3]
	s_mov_b32 m0, s34
	s_nop 0
	global_load_lds_dwordx4 v[134:135], off
	v_lshl_add_u64 v[134:135], v[158:159], 0, s[2:3]
	s_mov_b32 m0, s35
	s_nop 0
	global_load_lds_dwordx4 v[134:135], off
	s_waitcnt vmcnt(6)
	s_waitcnt lgkmcnt(0)
	s_barrier
	s_setprio 1
	s_waitcnt lgkmcnt(0)
	s_setprio 0
	s_setprio 1
	v_mfma_f32_16x16x32_bf16 v[52:55], v[198:201], v[214:217], v[52:55]
	v_mfma_f32_16x16x32_bf16 v[48:51], v[206:209], v[214:217], v[48:51]
	v_mfma_f32_16x16x32_bf16 v[36:39], v[198:201], v[222:225], v[36:39]
	v_mfma_f32_16x16x32_bf16 v[32:35], v[206:209], v[222:225], v[32:35]
	v_mfma_f32_16x16x32_bf16 v[20:23], v[198:201], v[230:233], v[20:23]
	v_mfma_f32_16x16x32_bf16 v[16:19], v[206:209], v[230:233], v[16:19]
	v_mfma_f32_16x16x32_bf16 v[4:7], v[198:201], v[238:241], v[4:7]
	v_mfma_f32_16x16x32_bf16 v[0:3], v[206:209], v[238:241], v[0:3]
	v_mfma_f32_16x16x32_bf16 v[52:55], v[202:205], v[218:221], v[52:55]
	v_mfma_f32_16x16x32_bf16 v[48:51], v[210:213], v[218:221], v[48:51]
	v_mfma_f32_16x16x32_bf16 v[36:39], v[202:205], v[226:229], v[36:39]
	v_mfma_f32_16x16x32_bf16 v[32:35], v[210:213], v[226:229], v[32:35]
	v_mfma_f32_16x16x32_bf16 v[20:23], v[202:205], v[234:237], v[20:23]
	v_mfma_f32_16x16x32_bf16 v[16:19], v[210:213], v[234:237], v[16:19]
	v_mfma_f32_16x16x32_bf16 v[4:7], v[202:205], v[242:245], v[4:7]
	v_mfma_f32_16x16x32_bf16 v[0:3], v[210:213], v[242:245], v[0:3]
	s_setprio 0
	s_barrier
	s_add_i32 s44, s44, 2
	s_add_u32 s18, s18, 0x100
	s_addc_u32 s19, s19, 0
	s_add_u32 s42, s42, 0x100
	s_addc_u32 s43, s43, 0
	s_cmp_gt_u32 s44, 13
	s_cbranch_scc0 .Lh1_B_160
	s_and_b64 vcc, exec, s[6:7]
	s_cbranch_vccz .Lh1_B_163
	s_barrier
.Lh1_B_163:
	v_lshl_add_u32 v148, s39, 8, v150
	v_max_f32_e32 v124, v124, v124
	v_max_f32_e32 v120, v120, v120
	v_max_f32_e32 v125, v125, v125
	v_max_f32_e32 v121, v121, v121
	v_max_f32_e32 v126, v126, v126
	v_max_f32_e32 v127, v127, v127
	v_lshl_or_b32 v134, s38, 8, v152
	v_ashrrev_i32_e32 v149, 31, v148
	v_max_f32_e32 v124, 0, v124
	v_max_f32_e32 v120, 0, v120
	v_max_f32_e32 v125, 0, v125
	v_max_f32_e32 v121, 0, v121
	v_max_f32_e32 v126, 0, v126
	v_max_f32_e32 v122, v122, v122
	v_max_f32_e32 v127, 0, v127
	v_max_f32_e32 v123, v123, v123
	v_lshlrev_b64 v[136:137], 13, v[148:149]
	v_pk_mul_f32 v[124:125], v[124:125], v[124:125]
	v_pk_mul_f32 v[120:121], v[120:121], v[120:121]
	v_max_f32_e32 v122, 0, v122
	v_max_f32_e32 v123, 0, v123
	v_pk_mul_f32 v[126:127], v[126:127], v[126:127]
	v_ashrrev_i32_e32 v135, 31, v134
	v_pk_mul_f32 v[154:155], v[122:123], v[122:123]
	v_cvt_pk_bf16_f32 v122, v124, v125
	v_cvt_pk_bf16_f32 v123, v126, v127
	v_cvt_pk_bf16_f32 v124, v120, v121
	v_lshl_add_u64 v[126:127], s[8:9], 0, v[136:137]
	v_lshlrev_b64 v[120:121], 1, v[134:135]
	v_max_f32_e32 v112, v112, v112
	v_max_f32_e32 v113, v113, v113
	v_cvt_pk_bf16_f32 v125, v154, v155
	v_lshl_add_u64 v[126:127], v[126:127], 0, v[120:121]
	v_max_f32_e32 v112, 0, v112
	v_max_f32_e32 v113, 0, v113
	v_max_f32_e32 v116, v116, v116
	v_max_f32_e32 v117, v117, v117
	v_pk_mul_f32 v[122:123], v[112:113], v[112:113]
	v_max_f32_e32 v113, v114, v114
	v_max_f32_e32 v112, v118, v118
	v_max_f32_e32 v114, 0, v113
	v_max_f32_e32 v113, v119, v119
	v_max_f32_e32 v115, v115, v115
	v_max_f32_e32 v116, 0, v116
	v_max_f32_e32 v117, 0, v117
	v_max_f32_e32 v112, 0, v112
	v_max_f32_e32 v113, 0, v113
	v_max_f32_e32 v115, 0, v115
	v_pk_mul_f32 v[116:117], v[116:117], v[116:117]
	v_pk_mul_f32 v[118:119], v[112:113], v[112:113]
	v_pk_mul_f32 v[124:125], v[114:115], v[114:115]
	v_max_f32_e32 v104, v104, v104
	v_max_f32_e32 v105, v105, v105
	v_cvt_pk_bf16_f32 v112, v116, v117
	v_cvt_pk_bf16_f32 v113, v118, v119
	v_cvt_pk_bf16_f32 v114, v122, v123
	v_cvt_pk_bf16_f32 v115, v124, v125
	v_max_f32_e32 v104, 0, v104
	v_max_f32_e32 v105, 0, v105
	global_store_dwordx4 v[126:127], v[112:115], off offset:256
	v_max_f32_e32 v108, v108, v108
	v_max_f32_e32 v109, v109, v109
	v_or_b32_e32 v112, 16, v148
	v_pk_mul_f32 v[114:115], v[104:105], v[104:105]
	v_max_f32_e32 v105, v106, v106
	v_ashrrev_i32_e32 v113, 31, v112
	v_max_f32_e32 v108, 0, v108
	v_max_f32_e32 v109, 0, v109
	v_max_f32_e32 v104, v110, v110
	v_max_f32_e32 v106, 0, v105
	v_max_f32_e32 v105, v111, v111
	v_max_f32_e32 v107, v107, v107
	v_lshlrev_b64 v[112:113], 13, v[112:113]
	v_pk_mul_f32 v[108:109], v[108:109], v[108:109]
	v_max_f32_e32 v104, 0, v104
	v_max_f32_e32 v105, 0, v105
	v_max_f32_e32 v107, 0, v107
	v_pk_mul_f32 v[110:111], v[104:105], v[104:105]
	v_pk_mul_f32 v[116:117], v[106:107], v[106:107]
	v_cvt_pk_bf16_f32 v104, v108, v109
	v_lshl_add_u64 v[108:109], s[8:9], 0, v[112:113]
	v_max_f32_e32 v96, v96, v96
	v_max_f32_e32 v97, v97, v97
	v_cvt_pk_bf16_f32 v105, v110, v111
	v_cvt_pk_bf16_f32 v106, v114, v115
	v_cvt_pk_bf16_f32 v107, v116, v117
	v_lshl_add_u64 v[108:109], v[108:109], 0, v[120:121]
	v_max_f32_e32 v96, 0, v96
	v_max_f32_e32 v97, 0, v97
	v_max_f32_e32 v100, v100, v100
	v_max_f32_e32 v101, v101, v101
	v_pk_mul_f32 v[104:105], v[96:97], v[96:97]
	v_max_f32_e32 v97, v98, v98
	v_max_f32_e32 v96, v102, v102
	v_max_f32_e32 v98, 0, v97
	v_max_f32_e32 v97, v103, v103
	v_max_f32_e32 v99, v99, v99
	v_max_f32_e32 v100, 0, v100
	v_max_f32_e32 v101, 0, v101
	v_max_f32_e32 v96, 0, v96
	v_max_f32_e32 v97, 0, v97
	v_max_f32_e32 v99, 0, v99
	v_pk_mul_f32 v[100:101], v[100:101], v[100:101]
	v_pk_mul_f32 v[102:103], v[96:97], v[96:97]
	v_pk_mul_f32 v[106:107], v[98:99], v[98:99]
	v_max_f32_e32 v88, v88, v88
	v_max_f32_e32 v89, v89, v89
	v_cvt_pk_bf16_f32 v96, v100, v101
	v_cvt_pk_bf16_f32 v97, v102, v103
	v_cvt_pk_bf16_f32 v98, v104, v105
	v_cvt_pk_bf16_f32 v99, v106, v107
	v_max_f32_e32 v88, 0, v88
	v_max_f32_e32 v89, 0, v89
	global_store_dwordx4 v[108:109], v[96:99], off offset:256
	v_max_f32_e32 v92, v92, v92
	v_max_f32_e32 v93, v93, v93
	v_or_b32_e32 v96, 32, v148
	v_pk_mul_f32 v[98:99], v[88:89], v[88:89]
	v_max_f32_e32 v89, v90, v90
	v_ashrrev_i32_e32 v97, 31, v96
	v_max_f32_e32 v92, 0, v92
	v_max_f32_e32 v93, 0, v93
	v_max_f32_e32 v88, v94, v94
	v_max_f32_e32 v90, 0, v89
	v_max_f32_e32 v89, v95, v95
	v_max_f32_e32 v91, v91, v91
	v_lshlrev_b64 v[96:97], 13, v[96:97]
	v_pk_mul_f32 v[92:93], v[92:93], v[92:93]
	v_max_f32_e32 v88, 0, v88
	v_max_f32_e32 v89, 0, v89
	v_max_f32_e32 v91, 0, v91
	v_pk_mul_f32 v[94:95], v[88:89], v[88:89]
	v_pk_mul_f32 v[100:101], v[90:91], v[90:91]
	v_cvt_pk_bf16_f32 v88, v92, v93
	v_lshl_add_u64 v[92:93], s[8:9], 0, v[96:97]
	v_max_f32_e32 v80, v80, v80
	v_max_f32_e32 v81, v81, v81
	v_cvt_pk_bf16_f32 v89, v94, v95
	v_cvt_pk_bf16_f32 v90, v98, v99
	v_cvt_pk_bf16_f32 v91, v100, v101
	v_lshl_add_u64 v[92:93], v[92:93], 0, v[120:121]
	v_max_f32_e32 v80, 0, v80
	v_max_f32_e32 v81, 0, v81
	v_max_f32_e32 v84, v84, v84
	v_max_f32_e32 v85, v85, v85
	v_pk_mul_f32 v[88:89], v[80:81], v[80:81]
	v_max_f32_e32 v81, v82, v82
	v_max_f32_e32 v80, v86, v86
	v_max_f32_e32 v82, 0, v81
	v_max_f32_e32 v81, v87, v87
	v_max_f32_e32 v83, v83, v83
	v_max_f32_e32 v84, 0, v84
	v_max_f32_e32 v85, 0, v85
	v_max_f32_e32 v80, 0, v80
	v_max_f32_e32 v81, 0, v81
	v_max_f32_e32 v83, 0, v83
	v_pk_mul_f32 v[84:85], v[84:85], v[84:85]
	v_pk_mul_f32 v[86:87], v[80:81], v[80:81]
	v_pk_mul_f32 v[90:91], v[82:83], v[82:83]
	v_max_f32_e32 v72, v72, v72
	v_max_f32_e32 v73, v73, v73
	v_cvt_pk_bf16_f32 v80, v84, v85
	v_cvt_pk_bf16_f32 v81, v86, v87
	v_cvt_pk_bf16_f32 v82, v88, v89
	v_cvt_pk_bf16_f32 v83, v90, v91
	v_max_f32_e32 v72, 0, v72
	v_max_f32_e32 v73, 0, v73
	global_store_dwordx4 v[92:93], v[80:83], off offset:256
	v_max_f32_e32 v76, v76, v76
	v_max_f32_e32 v77, v77, v77
	v_or_b32_e32 v80, 48, v148
	v_pk_mul_f32 v[82:83], v[72:73], v[72:73]
	v_max_f32_e32 v73, v74, v74
	v_ashrrev_i32_e32 v81, 31, v80
	v_max_f32_e32 v76, 0, v76
	v_max_f32_e32 v77, 0, v77
	v_max_f32_e32 v72, v78, v78
	v_max_f32_e32 v74, 0, v73
	v_max_f32_e32 v73, v79, v79
	v_max_f32_e32 v75, v75, v75
	v_lshlrev_b64 v[80:81], 13, v[80:81]
	v_pk_mul_f32 v[76:77], v[76:77], v[76:77]
	v_max_f32_e32 v72, 0, v72
	v_max_f32_e32 v73, 0, v73
	v_max_f32_e32 v75, 0, v75
	v_pk_mul_f32 v[78:79], v[72:73], v[72:73]
	v_pk_mul_f32 v[84:85], v[74:75], v[74:75]
	v_cvt_pk_bf16_f32 v72, v76, v77
	v_lshl_add_u64 v[76:77], s[8:9], 0, v[80:81]
	v_max_f32_e32 v64, v64, v64
	v_max_f32_e32 v65, v65, v65
	v_cvt_pk_bf16_f32 v73, v78, v79
	v_cvt_pk_bf16_f32 v74, v82, v83
	v_cvt_pk_bf16_f32 v75, v84, v85
	v_lshl_add_u64 v[76:77], v[76:77], 0, v[120:121]
	v_max_f32_e32 v64, 0, v64
	v_max_f32_e32 v65, 0, v65
	v_max_f32_e32 v68, v68, v68
	v_max_f32_e32 v69, v69, v69
	v_pk_mul_f32 v[72:73], v[64:65], v[64:65]
	v_max_f32_e32 v65, v66, v66
	v_max_f32_e32 v64, v70, v70
	v_max_f32_e32 v66, 0, v65
	v_max_f32_e32 v65, v71, v71
	v_max_f32_e32 v67, v67, v67
	v_max_f32_e32 v68, 0, v68
	v_max_f32_e32 v69, 0, v69
	v_max_f32_e32 v64, 0, v64
	v_max_f32_e32 v65, 0, v65
	v_max_f32_e32 v67, 0, v67
	v_pk_mul_f32 v[68:69], v[68:69], v[68:69]
	v_pk_mul_f32 v[70:71], v[64:65], v[64:65]
	v_pk_mul_f32 v[74:75], v[66:67], v[66:67]
	v_max_f32_e32 v56, v56, v56
	v_max_f32_e32 v57, v57, v57
	v_cvt_pk_bf16_f32 v64, v68, v69
	v_cvt_pk_bf16_f32 v65, v70, v71
	v_cvt_pk_bf16_f32 v66, v72, v73
	v_cvt_pk_bf16_f32 v67, v74, v75
	v_max_f32_e32 v56, 0, v56
	v_max_f32_e32 v57, 0, v57
	global_store_dwordx4 v[76:77], v[64:67], off offset:256
	v_max_f32_e32 v60, v60, v60
	v_max_f32_e32 v61, v61, v61
	v_add_u32_e32 v64, 0x80, v148
	v_pk_mul_f32 v[66:67], v[56:57], v[56:57]
	v_max_f32_e32 v57, v58, v58
	v_ashrrev_i32_e32 v65, 31, v64
	v_max_f32_e32 v60, 0, v60
	v_max_f32_e32 v61, 0, v61
	v_max_f32_e32 v56, v62, v62
	v_max_f32_e32 v58, 0, v57
	v_max_f32_e32 v57, v63, v63
	v_max_f32_e32 v59, v59, v59
	v_lshlrev_b64 v[64:65], 13, v[64:65]
	v_pk_mul_f32 v[60:61], v[60:61], v[60:61]
	v_max_f32_e32 v56, 0, v56
	v_max_f32_e32 v57, 0, v57
	v_max_f32_e32 v59, 0, v59
	v_pk_mul_f32 v[62:63], v[56:57], v[56:57]
	v_pk_mul_f32 v[68:69], v[58:59], v[58:59]
	v_cvt_pk_bf16_f32 v56, v60, v61
	v_lshl_add_u64 v[60:61], s[8:9], 0, v[64:65]
	v_max_f32_e32 v48, v48, v48
	v_max_f32_e32 v49, v49, v49
	v_cvt_pk_bf16_f32 v57, v62, v63
	v_cvt_pk_bf16_f32 v58, v66, v67
	v_cvt_pk_bf16_f32 v59, v68, v69
	v_lshl_add_u64 v[60:61], v[60:61], 0, v[120:121]
	v_max_f32_e32 v48, 0, v48
	v_max_f32_e32 v49, 0, v49
	v_max_f32_e32 v52, v52, v52
	v_max_f32_e32 v53, v53, v53
	v_pk_mul_f32 v[56:57], v[48:49], v[48:49]
	v_max_f32_e32 v49, v50, v50
	v_max_f32_e32 v48, v54, v54
	v_max_f32_e32 v50, 0, v49
	v_max_f32_e32 v49, v55, v55
	v_max_f32_e32 v51, v51, v51
	v_max_f32_e32 v52, 0, v52
	v_max_f32_e32 v53, 0, v53
	v_max_f32_e32 v48, 0, v48
	v_max_f32_e32 v49, 0, v49
	v_max_f32_e32 v51, 0, v51
	v_pk_mul_f32 v[52:53], v[52:53], v[52:53]
	v_pk_mul_f32 v[54:55], v[48:49], v[48:49]
	v_pk_mul_f32 v[58:59], v[50:51], v[50:51]
	v_max_f32_e32 v40, v40, v40
	v_max_f32_e32 v41, v41, v41
	v_cvt_pk_bf16_f32 v48, v52, v53
	v_cvt_pk_bf16_f32 v49, v54, v55
	v_cvt_pk_bf16_f32 v50, v56, v57
	v_cvt_pk_bf16_f32 v51, v58, v59
	v_max_f32_e32 v40, 0, v40
	v_max_f32_e32 v41, 0, v41
	global_store_dwordx4 v[60:61], v[48:51], off offset:256
	v_max_f32_e32 v44, v44, v44
	v_max_f32_e32 v45, v45, v45
	v_add_u32_e32 v48, 0x90, v148
	v_pk_mul_f32 v[50:51], v[40:41], v[40:41]
	v_max_f32_e32 v41, v42, v42
	v_ashrrev_i32_e32 v49, 31, v48
	v_max_f32_e32 v44, 0, v44
	v_max_f32_e32 v45, 0, v45
	v_max_f32_e32 v40, v46, v46
	v_max_f32_e32 v42, 0, v41
	v_max_f32_e32 v41, v47, v47
	v_max_f32_e32 v43, v43, v43
	v_lshlrev_b64 v[48:49], 13, v[48:49]
	v_pk_mul_f32 v[44:45], v[44:45], v[44:45]
	v_max_f32_e32 v40, 0, v40
	v_max_f32_e32 v41, 0, v41
	v_max_f32_e32 v43, 0, v43
	v_pk_mul_f32 v[46:47], v[40:41], v[40:41]
	v_pk_mul_f32 v[52:53], v[42:43], v[42:43]
	v_cvt_pk_bf16_f32 v40, v44, v45
	v_lshl_add_u64 v[44:45], s[8:9], 0, v[48:49]
	v_max_f32_e32 v32, v32, v32
	v_max_f32_e32 v33, v33, v33
	v_cvt_pk_bf16_f32 v41, v46, v47
	v_cvt_pk_bf16_f32 v42, v50, v51
	v_cvt_pk_bf16_f32 v43, v52, v53
	v_lshl_add_u64 v[44:45], v[44:45], 0, v[120:121]
	v_max_f32_e32 v32, 0, v32
	v_max_f32_e32 v33, 0, v33
	v_max_f32_e32 v36, v36, v36
	v_max_f32_e32 v37, v37, v37
	v_pk_mul_f32 v[40:41], v[32:33], v[32:33]
	v_max_f32_e32 v33, v34, v34
	v_max_f32_e32 v32, v38, v38
	v_max_f32_e32 v34, 0, v33
	v_max_f32_e32 v33, v39, v39
	v_max_f32_e32 v35, v35, v35
	v_max_f32_e32 v36, 0, v36
	v_max_f32_e32 v37, 0, v37
	v_max_f32_e32 v32, 0, v32
	v_max_f32_e32 v33, 0, v33
	v_max_f32_e32 v35, 0, v35
	v_pk_mul_f32 v[36:37], v[36:37], v[36:37]
	v_pk_mul_f32 v[38:39], v[32:33], v[32:33]
	v_pk_mul_f32 v[42:43], v[34:35], v[34:35]
	v_max_f32_e32 v24, v24, v24
	v_max_f32_e32 v25, v25, v25
	v_cvt_pk_bf16_f32 v32, v36, v37
	v_cvt_pk_bf16_f32 v33, v38, v39
	v_cvt_pk_bf16_f32 v34, v40, v41
	v_cvt_pk_bf16_f32 v35, v42, v43
	v_max_f32_e32 v24, 0, v24
	v_max_f32_e32 v25, 0, v25
	global_store_dwordx4 v[44:45], v[32:35], off offset:256
	v_max_f32_e32 v28, v28, v28
	v_max_f32_e32 v29, v29, v29
	v_add_u32_e32 v32, 0xa0, v148
	v_pk_mul_f32 v[34:35], v[24:25], v[24:25]
	v_max_f32_e32 v25, v26, v26
	v_ashrrev_i32_e32 v33, 31, v32
	v_max_f32_e32 v28, 0, v28
	v_max_f32_e32 v29, 0, v29
	v_max_f32_e32 v24, v30, v30
	v_max_f32_e32 v26, 0, v25
	v_max_f32_e32 v25, v31, v31
	v_max_f32_e32 v27, v27, v27
	v_lshlrev_b64 v[32:33], 13, v[32:33]
	v_pk_mul_f32 v[28:29], v[28:29], v[28:29]
	v_max_f32_e32 v24, 0, v24
	v_max_f32_e32 v25, 0, v25
	v_max_f32_e32 v27, 0, v27
	v_pk_mul_f32 v[30:31], v[24:25], v[24:25]
	v_pk_mul_f32 v[36:37], v[26:27], v[26:27]
	v_cvt_pk_bf16_f32 v24, v28, v29
	v_lshl_add_u64 v[28:29], s[8:9], 0, v[32:33]
	v_max_f32_e32 v16, v16, v16
	v_max_f32_e32 v17, v17, v17
	v_cvt_pk_bf16_f32 v25, v30, v31
	v_cvt_pk_bf16_f32 v26, v34, v35
	v_cvt_pk_bf16_f32 v27, v36, v37
	v_lshl_add_u64 v[28:29], v[28:29], 0, v[120:121]
	v_max_f32_e32 v16, 0, v16
	v_max_f32_e32 v17, 0, v17
	v_max_f32_e32 v20, v20, v20
	v_max_f32_e32 v21, v21, v21
	v_pk_mul_f32 v[24:25], v[16:17], v[16:17]
	v_max_f32_e32 v17, v18, v18
	v_max_f32_e32 v16, v22, v22
	v_max_f32_e32 v18, 0, v17
	v_max_f32_e32 v17, v23, v23
	v_max_f32_e32 v19, v19, v19
	v_max_f32_e32 v20, 0, v20
	v_max_f32_e32 v21, 0, v21
	v_max_f32_e32 v16, 0, v16
	v_max_f32_e32 v17, 0, v17
	v_max_f32_e32 v19, 0, v19
	v_pk_mul_f32 v[20:21], v[20:21], v[20:21]
	v_pk_mul_f32 v[22:23], v[16:17], v[16:17]
	v_pk_mul_f32 v[26:27], v[18:19], v[18:19]
	v_max_f32_e32 v8, v8, v8
	v_max_f32_e32 v9, v9, v9
	v_cvt_pk_bf16_f32 v16, v20, v21
	v_cvt_pk_bf16_f32 v17, v22, v23
	v_cvt_pk_bf16_f32 v18, v24, v25
	v_cvt_pk_bf16_f32 v19, v26, v27
	v_max_f32_e32 v8, 0, v8
	v_max_f32_e32 v9, 0, v9
	global_store_dwordx4 v[28:29], v[16:19], off offset:256
	v_max_f32_e32 v12, v12, v12
	v_max_f32_e32 v13, v13, v13
	v_add_u32_e32 v16, 0xb0, v148
	v_pk_mul_f32 v[18:19], v[8:9], v[8:9]
	v_max_f32_e32 v9, v10, v10
	v_ashrrev_i32_e32 v17, 31, v16
	v_max_f32_e32 v12, 0, v12
	v_max_f32_e32 v13, 0, v13
	v_max_f32_e32 v8, v14, v14
	v_max_f32_e32 v10, 0, v9
	v_max_f32_e32 v9, v15, v15
	v_max_f32_e32 v11, v11, v11
	v_lshlrev_b64 v[16:17], 13, v[16:17]
	v_pk_mul_f32 v[12:13], v[12:13], v[12:13]
	v_max_f32_e32 v8, 0, v8
	v_max_f32_e32 v9, 0, v9
	v_max_f32_e32 v11, 0, v11
	v_pk_mul_f32 v[14:15], v[8:9], v[8:9]
	v_pk_mul_f32 v[20:21], v[10:11], v[10:11]
	v_cvt_pk_bf16_f32 v8, v12, v13
	v_lshl_add_u64 v[12:13], s[8:9], 0, v[16:17]
	v_max_f32_e32 v0, v0, v0
	v_max_f32_e32 v1, v1, v1
	v_cvt_pk_bf16_f32 v9, v14, v15
	v_cvt_pk_bf16_f32 v10, v18, v19
	v_cvt_pk_bf16_f32 v11, v20, v21
	v_lshl_add_u64 v[12:13], v[12:13], 0, v[120:121]
	v_max_f32_e32 v0, 0, v0
	v_max_f32_e32 v1, 0, v1
	v_max_f32_e32 v4, v4, v4
	v_max_f32_e32 v5, v5, v5
	v_pk_mul_f32 v[8:9], v[0:1], v[0:1]
	v_max_f32_e32 v1, v2, v2
	v_max_f32_e32 v0, v6, v6
	v_max_f32_e32 v2, 0, v1
	v_max_f32_e32 v1, v7, v7
	v_max_f32_e32 v3, v3, v3
	v_max_f32_e32 v4, 0, v4
	v_max_f32_e32 v5, 0, v5
	v_max_f32_e32 v0, 0, v0
	v_max_f32_e32 v1, 0, v1
	v_max_f32_e32 v3, 0, v3
	v_pk_mul_f32 v[4:5], v[4:5], v[4:5]
	v_pk_mul_f32 v[6:7], v[0:1], v[0:1]
	v_pk_mul_f32 v[10:11], v[2:3], v[2:3]
	v_cvt_pk_bf16_f32 v0, v4, v5
	v_cvt_pk_bf16_f32 v1, v6, v7
	v_cvt_pk_bf16_f32 v2, v8, v9
	v_cvt_pk_bf16_f32 v3, v10, v11
	s_andn2_b64 vcc, exec, s[0:1]
	s_mov_b64 s[0:1], -1
	s_movk_i32 s48, 0x90
	global_store_dwordx4 v[12:13], v[0:3], off offset:256
	s_cbranch_vccnz .LBB0_156
	s_andn2_b64 vcc, exec, s[4:5]
	s_cbranch_vccnz .LBB0_155
	s_barrier
	s_branch .LBB0_155
